# NORM2 sample-row pass: the 8 head sum-of-squares loads, 4 partial-sum loads, gate and x issued together with counted waits instead of 13 serialized round trips
# baseline (speedup 1.0000x reference)
.LBB0_1179:
	s_add_i32 s16, s3, 0x4000
	s_ashr_i32 s10, s3, 4
	s_add_u32 s24, s0, s44
	s_addc_u32 s25, s1, s45
	global_load_dword v0, v209, s[24:25]
	global_load_dword v1, v209, s[24:25] offset:1024
	global_load_dword v30, v209, s[24:25] offset:2048
	global_load_dword v31, v209, s[24:25] offset:3072
	v_mov_b32_e32 v2, 0x39901000
	global_load_dword v32, v2, s[24:25]
	global_load_dword v33, v2, s[24:25] offset:1024
	global_load_dword v34, v2, s[24:25] offset:2048
	global_load_dword v35, v2, s[24:25] offset:3072
	v_lshl_add_u64 v[20:21], v[10:11], 0, s[44:45]
	s_ashr_i32 s17, s16, 31
	s_lshl_b64 s[16:17], s[16:17], 13
	s_add_i32 s14, s10, 8
	s_mul_hi_i32 s10, s14, 0xc000
	v_add_co_u32_e32 v14, vcc, 0x43c00000, v20
	s_nop 1
	v_addc_co_u32_e32 v15, vcc, 0, v21, vcc
	global_load_dwordx4 v[36:39], v[14:15], off
	v_add_co_u32_e32 v16, vcc, 0x43e00000, v20
	s_nop 1
	v_addc_co_u32_e32 v17, vcc, 0, v21, vcc
	global_load_dwordx4 v[40:43], v[16:17], off
	v_add_co_u32_e32 v14, vcc, 0x44000000, v20
	s_nop 1
	v_addc_co_u32_e32 v15, vcc, 0, v21, vcc
	global_load_dwordx4 v[44:47], v[14:15], off
	v_add_co_u32_e32 v16, vcc, 0x44200000, v20
	s_nop 1
	v_addc_co_u32_e32 v17, vcc, 0, v21, vcc
	global_load_dwordx4 v[48:51], v[16:17], off
	v_lshl_add_u64 v[60:61], v[4:5], 0, s[16:17]
	v_mov_b32_e32 v62, 0xc000
	v_mad_i64_i32 v[62:63], s[16:17], s14, v62, v[6:7]
	global_load_dwordx4 v[52:55], v[62:63], off
	global_load_dwordx4 v[56:59], v[60:61], off
	s_waitcnt vmcnt(13)
	v_add_f32_e32 v0, 0, v0
	s_waitcnt vmcnt(12)
	v_add_f32_e32 v0, v0, v1
	s_waitcnt vmcnt(11)
	v_add_f32_e32 v0, v0, v30
	s_waitcnt vmcnt(10)
	v_add_f32_e32 v0, v0, v31
	s_waitcnt vmcnt(9)
	v_add_f32_e32 v0, v0, v32
	s_waitcnt vmcnt(8)
	v_add_f32_e32 v0, v0, v33
	s_waitcnt vmcnt(7)
	v_add_f32_e32 v0, v0, v34
	s_waitcnt vmcnt(6)
	v_add_f32_e32 v0, v0, v35
	v_fmamk_f32 v0, v0, 0x3a800000, v200
	v_cmp_gt_f32_e32 vcc, s12, v0
	v_mul_f32_e32 v1, 0x4f800000, v0
	s_nop 0
	v_cndmask_b32_e32 v0, v0, v1, vcc
	v_sqrt_f32_e32 v1, v0
	s_nop 0
	v_add_u32_e32 v2, -1, v1
	v_fma_f32 v3, -v2, v1, v0
	v_cmp_ge_f32_e64 s[42:43], 0, v3
	v_add_u32_e32 v3, 1, v1
	s_nop 0
	v_cndmask_b32_e64 v2, v1, v2, s[42:43]
	v_fma_f32 v1, -v3, v1, v0
	v_cmp_lt_f32_e64 s[42:43], 0, v1
	s_nop 1
	v_cndmask_b32_e64 v1, v2, v3, s[42:43]
	v_mul_f32_e32 v2, 0x37800000, v1
	v_cndmask_b32_e32 v1, v1, v2, vcc
	v_cmp_class_f32_e32 vcc, v0, v201
	s_nop 1
	v_cndmask_b32_e32 v0, v1, v0, vcc
	v_div_scale_f32 v1, s[24:25], v0, v0, 1.0
	v_rcp_f32_e32 v2, v1
	s_nop 0
	v_fma_f32 v3, -v1, v2, 1.0
	v_fmac_f32_e32 v2, v3, v2
	v_div_scale_f32 v3, vcc, 1.0, v0, 1.0
	v_mul_f32_e32 v12, v3, v2
	v_fma_f32 v13, -v1, v12, v3
	v_fmac_f32_e32 v12, v13, v2
	v_fma_f32 v1, -v1, v12, v3
	v_div_fmas_f32 v1, v1, v2, v12
	v_div_fixup_f32 v18, v1, v0, 1.0
	s_mul_i32 s12, s14, 0xc000
	s_waitcnt vmcnt(5)
	v_pk_fma_f32 v[24:25], v[36:37], v[18:19], 0 op_sel_hi:[1,0,0]
	v_pk_fma_f32 v[22:23], v[38:39], v[18:19], 0 op_sel_hi:[1,0,0]
	s_waitcnt vmcnt(4)
	v_pk_fma_f32 v[24:25], v[40:41], v[18:19], v[24:25] op_sel_hi:[1,0,1]
	v_pk_fma_f32 v[18:19], v[42:43], v[18:19], v[22:23] op_sel_hi:[1,0,1]
	s_waitcnt vmcnt(3)
	v_pk_add_f32 v[22:23], v[24:25], v[44:45]
	v_pk_add_f32 v[18:19], v[18:19], v[46:47]
	s_waitcnt vmcnt(2)
	v_pk_add_f32 v[20:21], v[22:23], v[48:49]
	v_pk_add_f32 v[18:19], v[18:19], v[50:51]
	s_waitcnt vmcnt(0)
	v_pk_fma_f32 v[2:3], v[18:19], v[54:55], v[58:59]
	v_pk_fma_f32 v[0:1], v[20:21], v[52:53], v[56:57]
	v_mov_b32_e32 v12, v60
	v_mov_b32_e32 v13, v61
	v_mul_f32_e32 v15, v3, v3
	v_mul_f32_e32 v14, v1, v1
	v_fmac_f32_e32 v14, v0, v0
	v_fmac_f32_e32 v15, v2, v2
	v_add_f32_e32 v14, v14, v15
	ds_swizzle_b32 v15, v14 offset:swizzle(SWAP,1)
	s_waitcnt lgkmcnt(0)
	v_add_f32_e32 v14, v14, v15
	ds_swizzle_b32 v15, v14 offset:swizzle(SWAP,2)
	s_waitcnt lgkmcnt(0)
	v_add_f32_e32 v14, v14, v15
	ds_swizzle_b32 v15, v14 offset:swizzle(SWAP,4)
	s_waitcnt lgkmcnt(0)
	v_add_f32_e32 v14, v14, v15
	ds_swizzle_b32 v15, v14 offset:swizzle(SWAP,8)
	s_waitcnt lgkmcnt(0)
	v_add_f32_e32 v14, v14, v15
	ds_swizzle_b32 v15, v14 offset:swizzle(SWAP,16)
	s_waitcnt lgkmcnt(0)
	v_add_f32_e32 v14, v14, v15
	v_mov_b32_e32 v15, v14
	s_nop 1
	v_permlane32_swap_b32_e32 v14, v15
	s_and_saveexec_b64 s[16:17], s[40:41]
	s_cbranch_execz .LBB0_1178
	v_add_f32_e32 v14, v14, v15
	v_mov_b32_e32 v15, s2
	ds_write_b32 v15, v14
	s_branch .LBB0_1178
